# accumulator zeroing at every GEMM unit start uses 64-bit moves (63 v_mov_b64 + 1 v_mov_b32 instead of 127 v_mov_b32), on top of the dead DPP zero-mov removal
# speedup vs baseline: 1.0084x; 1.0017x over previous
;     __device__ __forceinline__ int a_row(const Unit& u) const { return (u.pm / 17) * 4096 + 254 * (u.pm % 17) - 2; }
; template <class Epi, class Sched, bool ALIGN_EPI = false, bool SP2 = false>
; __device__ __forceinline__ void gemm_phase(PG8_LAS unsigned char* lds, const Gemm g, const Sched& S, const Epi& E) {
;     ...
;         const char* nA = has_next ? (const char*)g.A + (long)S.a_row(nxt) * (long)(K * 2) : cA; const char* nB = has_next ? (const char*)g.Bt + (size_t)nxt.pn * tstep : cB;
;     ...
;         for (int a = 0; a < 2; ++a)
; #pragma unroll
;             for (int b = 0; b < 2; ++b)
; #pragma unroll
;                 for (int m = 0; m < 4; ++m)
; #pragma unroll
;                     for (int n = 0; n < 2; ++n) acc[a][b][m][n] = (f32x4){0.f, 0.f, 0.f, 0.f};
;         cur = nxt; cA = nA; cB = nB; ++ui;
.LBB0_86:
	s_lshl_b32 s78, s96, 8
	s_ashr_i32 s79, s78, 31
	s_lshl_b64 s[78:79], s[78:79], 12
	s_add_u32 s78, s13, s78
	s_addc_u32 s79, s24, s79
	s_and_b64 s[80:81], s[0:1], exec
	s_cselect_b32 s5, s79, s83
	s_cselect_b32 s88, s78, s82
	s_ashr_i32 s61, s60, 31
	s_lshl_b64 s[80:81], s[60:61], 20
	s_add_u32 s80, s14, s80
	s_addc_u32 s81, s15, s81
	s_and_b64 s[86:87], s[0:1], exec
	s_cselect_b32 s61, s81, s85
	s_cselect_b32 s89, s80, s84
	s_add_u32 s82, s82, 0x80080
	s_addc_u32 s83, s83, 0
	s_add_u32 s90, s84, 0x100
	v_mov_b32_e32 v0, 0
	s_addc_u32 s91, s85, 0
	s_mov_b32 s92, -2
	v_mov_b32_e32 v1, 0
	v_mov_b64_e32 v[2:3], 0
	v_mov_b64_e32 v[4:5], 0
	v_mov_b64_e32 v[6:7], 0
	v_mov_b64_e32 v[8:9], 0
	v_mov_b64_e32 v[10:11], 0
	v_mov_b64_e32 v[12:13], 0
	v_mov_b64_e32 v[14:15], 0
	v_mov_b64_e32 v[16:17], 0
	s_waitcnt vmcnt(0)
	v_mov_b64_e32 v[18:19], 0
	v_mov_b64_e32 v[20:21], 0
	v_mov_b64_e32 v[22:23], 0
	v_mov_b64_e32 v[24:25], 0
	v_mov_b64_e32 v[26:27], 0
	v_mov_b64_e32 v[28:29], 0
	v_mov_b64_e32 v[30:31], 0
	v_mov_b64_e32 v[64:65], 0
	v_mov_b64_e32 v[66:67], 0
	v_mov_b64_e32 v[68:69], 0
	v_mov_b64_e32 v[70:71], 0
	v_mov_b64_e32 v[72:73], 0
	v_mov_b64_e32 v[74:75], 0
	v_mov_b64_e32 v[76:77], 0
	v_mov_b64_e32 v[78:79], 0
	v_mov_b64_e32 v[80:81], 0
	v_mov_b64_e32 v[82:83], 0
	v_mov_b64_e32 v[84:85], 0
	v_mov_b64_e32 v[86:87], 0
	v_mov_b64_e32 v[88:89], 0
	v_mov_b64_e32 v[90:91], 0
	v_mov_b64_e32 v[92:93], 0
	v_mov_b64_e32 v[94:95], 0
	v_mov_b64_e32 v[32:33], 0
	v_mov_b64_e32 v[34:35], 0
	v_mov_b64_e32 v[36:37], 0
	v_mov_b64_e32 v[38:39], 0
	v_mov_b64_e32 v[40:41], 0
	v_mov_b64_e32 v[42:43], 0
	v_mov_b64_e32 v[44:45], 0
	v_mov_b64_e32 v[46:47], 0
	v_mov_b64_e32 v[48:49], 0
	v_mov_b64_e32 v[50:51], 0
	v_mov_b64_e32 v[52:53], 0
	v_mov_b64_e32 v[54:55], 0
	v_mov_b64_e32 v[56:57], 0
	v_mov_b64_e32 v[58:59], 0
	v_mov_b64_e32 v[60:61], 0
	v_mov_b64_e32 v[62:63], 0
	v_mov_b64_e32 v[96:97], 0
	v_mov_b64_e32 v[98:99], 0
	v_mov_b64_e32 v[100:101], 0
	v_mov_b64_e32 v[102:103], 0
	v_mov_b64_e32 v[104:105], 0
	v_mov_b64_e32 v[106:107], 0
	v_mov_b64_e32 v[108:109], 0
	v_mov_b64_e32 v[110:111], 0
	v_mov_b64_e32 v[112:113], 0
	v_mov_b64_e32 v[114:115], 0
	v_mov_b64_e32 v[116:117], 0
	v_mov_b64_e32 v[118:119], 0
	v_mov_b64_e32 v[120:121], 0
	v_mov_b64_e32 v[122:123], 0
	v_mov_b64_e32 v[124:125], 0
	v_mov_b64_e32 v[126:127], 0

; template <class Epi, class Sched, bool ALIGN_EPI = false, bool SP2 = false>
; __device__ __forceinline__ void gemm_phase(PG8_LAS unsigned char* lds, const Gemm g, const Sched& S, const Epi& E) {
;     ...
;         for (int a = 0; a < 2; ++a)
; #pragma unroll
;             for (int b = 0; b < 2; ++b)
; #pragma unroll
;                 for (int m = 0; m < 4; ++m)
; #pragma unroll
;                     for (int n = 0; n < 2; ++n) acc[a][b][m][n] = (f32x4){0.f, 0.f, 0.f, 0.f};
;         cur = nxt; cA = nA; cB = nB; ++ui;
.LBB0_351:
	s_lshl_b32 s38, s62, 8
	s_ashr_i32 s39, s38, 31
	s_lshl_b64 s[38:39], s[38:39], 11
	s_add_u32 s38, s14, s38
	s_addc_u32 s39, s15, s39
	s_and_b64 s[40:41], s[0:1], exec
	s_cselect_b32 s65, s39, s47
	s_cselect_b32 s66, s38, s46
	s_ashr_i32 s27, s26, 31
	s_lshl_b64 s[40:41], s[26:27], 19
	s_add_u32 s40, s16, s40
	s_addc_u32 s41, s17, s41
	s_and_b64 s[54:55], s[0:1], exec
	s_cselect_b32 s27, s41, s49
	s_cselect_b32 s67, s40, s48
	s_add_u32 s46, s46, 0x40080
	s_addc_u32 s47, s47, 0
	s_add_u32 s68, s48, 0x100
	v_mov_b32_e32 v0, 0
	s_addc_u32 s69, s49, 0
	s_mov_b32 s70, -2
	v_mov_b32_e32 v1, 0
	v_mov_b64_e32 v[2:3], 0
	v_mov_b64_e32 v[4:5], 0
	v_mov_b64_e32 v[6:7], 0
	v_mov_b64_e32 v[12:13], 0
	v_mov_b64_e32 v[14:15], 0
	v_mov_b64_e32 v[20:21], 0
	v_mov_b64_e32 v[22:23], 0
	v_mov_b64_e32 v[28:29], 0
	v_mov_b64_e32 v[30:31], 0
	v_mov_b64_e32 v[36:37], 0
	v_mov_b64_e32 v[38:39], 0
	v_mov_b64_e32 v[44:45], 0
	v_mov_b64_e32 v[46:47], 0
	v_mov_b64_e32 v[52:53], 0
	v_mov_b64_e32 v[54:55], 0
	v_mov_b64_e32 v[8:9], 0
	v_mov_b64_e32 v[10:11], 0
	v_mov_b64_e32 v[16:17], 0
	v_mov_b64_e32 v[18:19], 0
	v_mov_b64_e32 v[24:25], 0
	v_mov_b64_e32 v[26:27], 0
	v_mov_b64_e32 v[32:33], 0
	v_mov_b64_e32 v[34:35], 0
	v_mov_b64_e32 v[40:41], 0
	v_mov_b64_e32 v[42:43], 0
	v_mov_b64_e32 v[48:49], 0
	v_mov_b64_e32 v[50:51], 0
	v_mov_b64_e32 v[56:57], 0
	v_mov_b64_e32 v[58:59], 0
	v_mov_b64_e32 v[60:61], 0
	v_mov_b64_e32 v[62:63], 0
	v_mov_b64_e32 v[64:65], 0
	v_mov_b64_e32 v[66:67], 0
	v_mov_b64_e32 v[68:69], 0
	v_mov_b64_e32 v[70:71], 0
	v_mov_b64_e32 v[76:77], 0
	v_mov_b64_e32 v[78:79], 0
	v_mov_b64_e32 v[84:85], 0
	v_mov_b64_e32 v[86:87], 0
	v_mov_b64_e32 v[92:93], 0
	v_mov_b64_e32 v[94:95], 0
	v_mov_b64_e32 v[100:101], 0
	v_mov_b64_e32 v[102:103], 0
	v_mov_b64_e32 v[112:113], 0
	v_mov_b64_e32 v[114:115], 0
	v_mov_b64_e32 v[116:117], 0
	v_mov_b64_e32 v[118:119], 0
	v_mov_b64_e32 v[72:73], 0
	v_mov_b64_e32 v[74:75], 0
	v_mov_b64_e32 v[80:81], 0
	v_mov_b64_e32 v[82:83], 0
	v_mov_b64_e32 v[88:89], 0
	v_mov_b64_e32 v[90:91], 0
	v_mov_b64_e32 v[96:97], 0
	v_mov_b64_e32 v[98:99], 0
	v_mov_b64_e32 v[104:105], 0
	v_mov_b64_e32 v[106:107], 0
	v_mov_b64_e32 v[108:109], 0
	v_mov_b64_e32 v[110:111], 0
	v_mov_b64_e32 v[120:121], 0
	v_mov_b64_e32 v[122:123], 0
	v_mov_b64_e32 v[124:125], 0
	v_mov_b64_e32 v[126:127], 0

; template <class Epi, class Sched, bool ALIGN_EPI = false, bool SP2 = false>
; __device__ __forceinline__ void gemm_phase(PG8_LAS unsigned char* lds, const Gemm g, const Sched& S, const Epi& E) {
;     ...
;         for (int a = 0; a < 2; ++a)
; #pragma unroll
;             for (int b = 0; b < 2; ++b)
; #pragma unroll
;                 for (int m = 0; m < 4; ++m)
; #pragma unroll
;                     for (int n = 0; n < 2; ++n) acc[a][b][m][n] = (f32x4){0.f, 0.f, 0.f, 0.f};
.LBB0_381:
	s_add_u32 s80, s58, 0x100
	v_mov_b32_e32 v0, 0
	s_addc_u32 s81, s59, 0
	s_mov_b32 s82, -2
	v_mov_b32_e32 v1, 0
	v_mov_b64_e32 v[2:3], 0
	v_mov_b64_e32 v[4:5], 0
	v_mov_b64_e32 v[6:7], 0
	v_mov_b64_e32 v[16:17], 0
	v_mov_b64_e32 v[18:19], 0
	v_mov_b64_e32 v[20:21], 0
	v_mov_b64_e32 v[22:23], 0
	v_mov_b64_e32 v[32:33], 0
	v_mov_b64_e32 v[34:35], 0
	v_mov_b64_e32 v[36:37], 0
	v_mov_b64_e32 v[38:39], 0
	v_mov_b64_e32 v[48:49], 0
	v_mov_b64_e32 v[50:51], 0
	v_mov_b64_e32 v[52:53], 0
	v_mov_b64_e32 v[54:55], 0
	v_mov_b64_e32 v[8:9], 0
	v_mov_b64_e32 v[10:11], 0
	v_mov_b64_e32 v[12:13], 0
	v_mov_b64_e32 v[14:15], 0
	v_mov_b64_e32 v[24:25], 0
	v_mov_b64_e32 v[26:27], 0
	v_mov_b64_e32 v[28:29], 0
	v_mov_b64_e32 v[30:31], 0
	v_mov_b64_e32 v[40:41], 0
	v_mov_b64_e32 v[42:43], 0
	v_mov_b64_e32 v[44:45], 0
	v_mov_b64_e32 v[46:47], 0
	v_mov_b64_e32 v[56:57], 0
	v_mov_b64_e32 v[58:59], 0
	v_mov_b64_e32 v[60:61], 0
	v_mov_b64_e32 v[62:63], 0
	v_mov_b64_e32 v[64:65], 0
	v_mov_b64_e32 v[66:67], 0
	v_mov_b64_e32 v[68:69], 0
	v_mov_b64_e32 v[70:71], 0
	v_mov_b64_e32 v[80:81], 0
	v_mov_b64_e32 v[82:83], 0
	v_mov_b64_e32 v[84:85], 0
	v_mov_b64_e32 v[86:87], 0
	v_mov_b64_e32 v[96:97], 0
	v_mov_b64_e32 v[98:99], 0
	v_mov_b64_e32 v[100:101], 0
	v_mov_b64_e32 v[102:103], 0
	v_mov_b64_e32 v[112:113], 0
	v_mov_b64_e32 v[114:115], 0
	v_mov_b64_e32 v[116:117], 0
	v_mov_b64_e32 v[118:119], 0
	v_mov_b64_e32 v[72:73], 0
	v_mov_b64_e32 v[74:75], 0
	v_mov_b64_e32 v[76:77], 0
	v_mov_b64_e32 v[78:79], 0
	v_mov_b64_e32 v[88:89], 0
	v_mov_b64_e32 v[90:91], 0
	v_mov_b64_e32 v[92:93], 0
	v_mov_b64_e32 v[94:95], 0
	v_mov_b64_e32 v[104:105], 0
	v_mov_b64_e32 v[106:107], 0
	v_mov_b64_e32 v[108:109], 0
	v_mov_b64_e32 v[110:111], 0
	v_mov_b64_e32 v[120:121], 0
	v_mov_b64_e32 v[122:123], 0
	v_mov_b64_e32 v[124:125], 0
	v_mov_b64_e32 v[126:127], 0

; template <class Epi, class Sched, bool ALIGN_EPI = false, bool SP2 = false>
; __device__ __forceinline__ void gemm_phase(PG8_LAS unsigned char* lds, const Gemm g, const Sched& S, const Epi& E) {
;     ...
;         for (int a = 0; a < 2; ++a)
; #pragma unroll
;             for (int b = 0; b < 2; ++b)
; #pragma unroll
;                 for (int m = 0; m < 4; ++m)
; #pragma unroll
;                     for (int n = 0; n < 2; ++n) acc[a][b][m][n] = (f32x4){0.f, 0.f, 0.f, 0.f};
;         cur = nxt; cA = nA; cB = nB; ++ui;
.LBB0_443:
	s_lshl_b32 s42, s68, 8
	s_ashr_i32 s43, s42, 31
	s_lshl_b64 s[42:43], s[42:43], 10
	s_add_u32 s42, s13, s42
	s_addc_u32 s43, s24, s43
	s_and_b64 s[44:45], s[4:5], exec
	s_cselect_b32 s47, s43, s49
	s_cselect_b32 s70, s42, s48
	s_ashr_i32 s41, s40, 31
	s_lshl_b64 s[44:45], s[40:41], 18
	s_add_u32 s44, s22, s44
	s_addc_u32 s45, s23, s45
	s_and_b64 s[56:57], s[4:5], exec
	s_cselect_b32 s41, s45, s55
	s_cselect_b32 s71, s44, s54
	s_add_u32 s48, s48, 0x20080
	s_addc_u32 s49, s49, 0
	s_add_u32 s72, s54, 0x100
	v_mov_b32_e32 v0, 0
	s_addc_u32 s73, s55, 0
	s_mov_b32 s74, -2
	v_mov_b32_e32 v1, 0
	v_mov_b64_e32 v[2:3], 0
	v_mov_b64_e32 v[4:5], 0
	v_mov_b64_e32 v[6:7], 0
	v_mov_b64_e32 v[16:17], 0
	v_mov_b64_e32 v[18:19], 0
	v_mov_b64_e32 v[20:21], 0
	v_mov_b64_e32 v[22:23], 0
	v_mov_b64_e32 v[32:33], 0
	v_mov_b64_e32 v[34:35], 0
	v_mov_b64_e32 v[36:37], 0
	v_mov_b64_e32 v[38:39], 0
	v_mov_b64_e32 v[48:49], 0
	v_mov_b64_e32 v[50:51], 0
	v_mov_b64_e32 v[52:53], 0
	v_mov_b64_e32 v[54:55], 0
	v_mov_b64_e32 v[8:9], 0
	v_mov_b64_e32 v[10:11], 0
	v_mov_b64_e32 v[12:13], 0
	v_mov_b64_e32 v[14:15], 0
	v_mov_b64_e32 v[24:25], 0
	v_mov_b64_e32 v[26:27], 0
	v_mov_b64_e32 v[28:29], 0
	v_mov_b64_e32 v[30:31], 0
	v_mov_b64_e32 v[40:41], 0
	v_mov_b64_e32 v[42:43], 0
	v_mov_b64_e32 v[44:45], 0
	v_mov_b64_e32 v[46:47], 0
	v_mov_b64_e32 v[56:57], 0
	v_mov_b64_e32 v[58:59], 0
	v_mov_b64_e32 v[60:61], 0
	v_mov_b64_e32 v[62:63], 0
	v_mov_b64_e32 v[64:65], 0
	v_mov_b64_e32 v[66:67], 0
	v_mov_b64_e32 v[68:69], 0
	v_mov_b64_e32 v[70:71], 0
	v_mov_b64_e32 v[80:81], 0
	v_mov_b64_e32 v[82:83], 0
	v_mov_b64_e32 v[84:85], 0
	v_mov_b64_e32 v[86:87], 0
	v_mov_b64_e32 v[96:97], 0
	v_mov_b64_e32 v[98:99], 0
	v_mov_b64_e32 v[100:101], 0
	v_mov_b64_e32 v[102:103], 0
	v_mov_b64_e32 v[112:113], 0
	v_mov_b64_e32 v[114:115], 0
	v_mov_b64_e32 v[116:117], 0
	v_mov_b64_e32 v[118:119], 0
	v_mov_b64_e32 v[72:73], 0
	v_mov_b64_e32 v[74:75], 0
	v_mov_b64_e32 v[76:77], 0
	v_mov_b64_e32 v[78:79], 0
	v_mov_b64_e32 v[88:89], 0
	v_mov_b64_e32 v[90:91], 0
	v_mov_b64_e32 v[92:93], 0
	v_mov_b64_e32 v[94:95], 0
	v_mov_b64_e32 v[104:105], 0
	v_mov_b64_e32 v[106:107], 0
	v_mov_b64_e32 v[108:109], 0
	v_mov_b64_e32 v[110:111], 0
	v_mov_b64_e32 v[120:121], 0
	v_mov_b64_e32 v[122:123], 0
	v_mov_b64_e32 v[124:125], 0
	v_mov_b64_e32 v[126:127], 0
	s_waitcnt vmcnt(0)

; template <class Epi, class Sched, bool ALIGN_EPI = false, bool SP2 = false>
; __device__ __forceinline__ void gemm_phase(PG8_LAS unsigned char* lds, const Gemm g, const Sched& S, const Epi& E) {
;     ...
;         for (int a = 0; a < 2; ++a)
; #pragma unroll
;             for (int b = 0; b < 2; ++b)
; #pragma unroll
;                 for (int m = 0; m < 4; ++m)
; #pragma unroll
;                     for (int n = 0; n < 2; ++n) acc[a][b][m][n] = (f32x4){0.f, 0.f, 0.f, 0.f};
;         cur = nxt; cA = nA; cB = nB; ++ui;
.LBB0_631:
	s_lshl_b32 s40, s58, 8
	s_ashr_i32 s41, s40, 31
	s_lshl_b64 s[40:41], s[40:41], 12
	s_add_u32 s40, s14, s40
	s_addc_u32 s41, s15, s41
	s_and_b64 s[42:43], s[4:5], exec
	s_cselect_b32 s1, s41, s45
	s_cselect_b32 s60, s40, s44
	s_ashr_i32 s23, s22, 31
	s_lshl_b64 s[42:43], s[22:23], 20
	s_add_u32 s42, s78, s42
	s_addc_u32 s43, s79, s43
	s_and_b64 s[48:49], s[4:5], exec
	s_cselect_b32 s23, s43, s47
	s_cselect_b32 s61, s42, s46
	s_add_u32 s44, s44, 0x80080
	s_addc_u32 s45, s45, 0
	s_add_u32 s62, s46, 0x100
	v_mov_b32_e32 v0, 0
	s_addc_u32 s63, s47, 0
	s_mov_b32 s64, -2
	v_mov_b32_e32 v1, 0
	v_mov_b64_e32 v[2:3], 0
	v_mov_b64_e32 v[4:5], 0
	v_mov_b64_e32 v[6:7], 0
	v_mov_b64_e32 v[12:13], 0
	v_mov_b64_e32 v[14:15], 0
	v_mov_b64_e32 v[20:21], 0
	v_mov_b64_e32 v[22:23], 0
	v_mov_b64_e32 v[28:29], 0
	v_mov_b64_e32 v[30:31], 0
	v_mov_b64_e32 v[36:37], 0
	v_mov_b64_e32 v[38:39], 0
	v_mov_b64_e32 v[44:45], 0
	v_mov_b64_e32 v[46:47], 0
	v_mov_b64_e32 v[52:53], 0
	v_mov_b64_e32 v[54:55], 0
	v_mov_b64_e32 v[8:9], 0
	v_mov_b64_e32 v[10:11], 0
	v_mov_b64_e32 v[16:17], 0
	v_mov_b64_e32 v[18:19], 0
	v_mov_b64_e32 v[24:25], 0
	v_mov_b64_e32 v[26:27], 0
	v_mov_b64_e32 v[32:33], 0
	v_mov_b64_e32 v[34:35], 0
	v_mov_b64_e32 v[40:41], 0
	v_mov_b64_e32 v[42:43], 0
	v_mov_b64_e32 v[48:49], 0
	v_mov_b64_e32 v[50:51], 0
	v_mov_b64_e32 v[56:57], 0
	v_mov_b64_e32 v[58:59], 0
	v_mov_b64_e32 v[60:61], 0
	v_mov_b64_e32 v[62:63], 0
	v_mov_b64_e32 v[64:65], 0
	v_mov_b64_e32 v[66:67], 0
	v_mov_b64_e32 v[68:69], 0
	v_mov_b64_e32 v[70:71], 0
	v_mov_b64_e32 v[76:77], 0
	v_mov_b64_e32 v[78:79], 0
	v_mov_b64_e32 v[84:85], 0
	v_mov_b64_e32 v[86:87], 0
	v_mov_b64_e32 v[92:93], 0
	v_mov_b64_e32 v[94:95], 0
	v_mov_b64_e32 v[100:101], 0
	v_mov_b64_e32 v[102:103], 0
	v_mov_b64_e32 v[108:109], 0
	v_mov_b64_e32 v[110:111], 0
	s_waitcnt vmcnt(0)
	v_mov_b64_e32 v[116:117], 0
	v_mov_b64_e32 v[118:119], 0
	v_mov_b64_e32 v[72:73], 0
	v_mov_b64_e32 v[74:75], 0
	v_mov_b64_e32 v[80:81], 0
	v_mov_b64_e32 v[82:83], 0
	v_mov_b64_e32 v[88:89], 0
	v_mov_b64_e32 v[90:91], 0
	v_mov_b64_e32 v[96:97], 0
	v_mov_b64_e32 v[98:99], 0
	v_mov_b64_e32 v[104:105], 0
	v_mov_b64_e32 v[106:107], 0
	v_mov_b64_e32 v[112:113], 0
	v_mov_b64_e32 v[114:115], 0
	v_mov_b64_e32 v[120:121], 0
	v_mov_b64_e32 v[122:123], 0
	v_mov_b64_e32 v[124:125], 0
	v_mov_b64_e32 v[126:127], 0

; template <class Epi, class Sched, bool ALIGN_EPI = false, bool SP2 = false>
; __device__ __forceinline__ void gemm_phase(PG8_LAS unsigned char* lds, const Gemm g, const Sched& S, const Epi& E) {
;     ...
;         for (int a = 0; a < 2; ++a)
; #pragma unroll
;             for (int b = 0; b < 2; ++b)
; #pragma unroll
;                 for (int m = 0; m < 4; ++m)
; #pragma unroll
;                     for (int n = 0; n < 2; ++n) acc[a][b][m][n] = (f32x4){0.f, 0.f, 0.f, 0.f};
;         cur = nxt; cA = nA; cB = nB; ++ui;
.LBB0_802:
	s_lshl_b32 s14, s57, 8
	s_ashr_i32 s15, s14, 31
	s_lshl_b64 s[14:15], s[14:15], 12
	s_add_u32 s14, s16, s14
	s_addc_u32 s15, s17, s15
	s_and_b64 s[18:19], s[6:7], exec
	s_cselect_b32 s21, s15, s23
	s_cselect_b32 s59, s14, s22
	s_ashr_i32 s13, s12, 31
	s_lshl_b64 s[18:19], s[12:13], 20
	s_add_u32 s18, s76, s18
	s_addc_u32 s19, s77, s19
	s_and_b64 s[46:47], s[6:7], exec
	s_cselect_b32 s13, s19, s45
	s_cselect_b32 s60, s18, s44
	s_add_u32 s22, s22, 0x80080
	s_addc_u32 s23, s23, 0
	s_add_u32 s61, s44, 0x100
	v_mov_b32_e32 v0, 0
	s_addc_u32 s62, s45, 0
	s_mov_b32 s63, -2
	v_mov_b32_e32 v1, 0
	v_mov_b64_e32 v[2:3], 0
	v_mov_b64_e32 v[4:5], 0
	v_mov_b64_e32 v[6:7], 0
	v_mov_b64_e32 v[16:17], 0
	v_mov_b64_e32 v[18:19], 0
	v_mov_b64_e32 v[20:21], 0
	v_mov_b64_e32 v[22:23], 0
	v_mov_b64_e32 v[32:33], 0
	v_mov_b64_e32 v[34:35], 0
	v_mov_b64_e32 v[36:37], 0
	v_mov_b64_e32 v[38:39], 0
	v_mov_b64_e32 v[48:49], 0
	v_mov_b64_e32 v[50:51], 0
	v_mov_b64_e32 v[52:53], 0
	v_mov_b64_e32 v[54:55], 0
	v_mov_b64_e32 v[8:9], 0
	v_mov_b64_e32 v[10:11], 0
	v_mov_b64_e32 v[12:13], 0
	v_mov_b64_e32 v[14:15], 0
	v_mov_b64_e32 v[24:25], 0
	v_mov_b64_e32 v[26:27], 0
	v_mov_b64_e32 v[28:29], 0
	v_mov_b64_e32 v[30:31], 0
	v_mov_b64_e32 v[40:41], 0
	v_mov_b64_e32 v[42:43], 0
	v_mov_b64_e32 v[44:45], 0
	v_mov_b64_e32 v[46:47], 0
	v_mov_b64_e32 v[56:57], 0
	v_mov_b64_e32 v[58:59], 0
	v_mov_b64_e32 v[60:61], 0
	v_mov_b64_e32 v[62:63], 0
	v_mov_b64_e32 v[64:65], 0
	v_mov_b64_e32 v[66:67], 0
	v_mov_b64_e32 v[68:69], 0
	v_mov_b64_e32 v[70:71], 0
	v_mov_b64_e32 v[80:81], 0
	v_mov_b64_e32 v[82:83], 0
	v_mov_b64_e32 v[84:85], 0
	v_mov_b64_e32 v[86:87], 0
	v_mov_b64_e32 v[96:97], 0
	v_mov_b64_e32 v[98:99], 0
	v_mov_b64_e32 v[100:101], 0
	v_mov_b64_e32 v[102:103], 0
	v_mov_b64_e32 v[112:113], 0
	v_mov_b64_e32 v[114:115], 0
	s_waitcnt vmcnt(0)
	v_mov_b64_e32 v[116:117], 0
	v_mov_b64_e32 v[118:119], 0
	v_mov_b64_e32 v[72:73], 0
	v_mov_b64_e32 v[74:75], 0
	v_mov_b64_e32 v[76:77], 0
	v_mov_b64_e32 v[78:79], 0
	v_mov_b64_e32 v[88:89], 0
	v_mov_b64_e32 v[90:91], 0
	v_mov_b64_e32 v[92:93], 0
	v_mov_b64_e32 v[94:95], 0
	v_mov_b64_e32 v[104:105], 0
	v_mov_b64_e32 v[106:107], 0
	v_mov_b64_e32 v[108:109], 0
	v_mov_b64_e32 v[110:111], 0
	v_mov_b64_e32 v[120:121], 0
	v_mov_b64_e32 v[122:123], 0
	v_mov_b64_e32 v[124:125], 0
	v_mov_b64_e32 v[126:127], 0

; template <class Epi, class Sched, bool ALIGN_EPI = false, bool SP2 = false>
; __device__ __forceinline__ void gemm_phase(PG8_LAS unsigned char* lds, const Gemm g, const Sched& S, const Epi& E) {
;     ...
;         for (int a = 0; a < 2; ++a)
; #pragma unroll
;             for (int b = 0; b < 2; ++b)
; #pragma unroll
;                 for (int m = 0; m < 4; ++m)
; #pragma unroll
;                     for (int n = 0; n < 2; ++n) acc[a][b][m][n] = (f32x4){0.f, 0.f, 0.f, 0.f};
;         cur = nxt; cA = nA; cB = nB; ++ui;
.LBB0_888:
	s_ashr_i32 s59, s58, 31
	s_lshl_b64 s[62:63], s[58:59], 20
	s_add_u32 s62, s38, s62
	s_addc_u32 s63, s39, s63
	s_and_b64 s[0:1], s[0:1], exec
	s_cselect_b32 s59, s63, s67
	s_cselect_b32 s65, s62, s66
	s_add_u32 s0, s76, 0x80080
	s_addc_u32 s1, s77, 0
	s_add_u32 s72, s66, 0x100
	v_mov_b32_e32 v0, 0
	s_addc_u32 s73, s67, 0
	s_mov_b32 s74, -2
	v_mov_b32_e32 v1, 0
	v_mov_b64_e32 v[2:3], 0
	v_mov_b64_e32 v[64:65], 0
	v_mov_b64_e32 v[66:67], 0
	v_mov_b64_e32 v[8:9], 0
	v_mov_b64_e32 v[10:11], 0
	v_mov_b64_e32 v[104:105], 0
	v_mov_b64_e32 v[106:107], 0
	v_mov_b64_e32 v[16:17], 0
	v_mov_b64_e32 v[18:19], 0
	v_mov_b64_e32 v[112:113], 0
	v_mov_b64_e32 v[114:115], 0
	v_mov_b64_e32 v[24:25], 0
	v_mov_b64_e32 v[26:27], 0
	v_mov_b64_e32 v[140:141], 0
	v_mov_b64_e32 v[142:143], 0
	v_mov_b64_e32 v[4:5], 0
	v_mov_b64_e32 v[6:7], 0
	v_mov_b64_e32 v[76:77], 0
	v_mov_b64_e32 v[78:79], 0
	v_mov_b64_e32 v[12:13], 0
	v_mov_b64_e32 v[14:15], 0
	v_mov_b64_e32 v[108:109], 0
	v_mov_b64_e32 v[110:111], 0
	v_mov_b64_e32 v[20:21], 0
	v_mov_b64_e32 v[22:23], 0
	s_waitcnt vmcnt(0)
	v_mov_b64_e32 v[116:117], 0
	v_mov_b64_e32 v[118:119], 0
	v_mov_b64_e32 v[28:29], 0
	v_mov_b64_e32 v[30:31], 0
	v_mov_b64_e32 v[156:157], 0
	v_mov_b64_e32 v[158:159], 0
	v_mov_b64_e32 v[32:33], 0
	v_mov_b64_e32 v[34:35], 0
	v_mov_b64_e32 v[68:69], 0
	v_mov_b64_e32 v[70:71], 0
	v_mov_b64_e32 v[40:41], 0
	v_mov_b64_e32 v[42:43], 0
	v_mov_b64_e32 v[80:81], 0
	v_mov_b64_e32 v[82:83], 0
	v_mov_b64_e32 v[48:49], 0
	v_mov_b64_e32 v[50:51], 0
	v_mov_b64_e32 v[88:89], 0
	v_mov_b64_e32 v[90:91], 0
	v_mov_b64_e32 v[56:57], 0
	v_mov_b64_e32 v[58:59], 0
	v_mov_b64_e32 v[96:97], 0
	v_mov_b64_e32 v[98:99], 0
	v_mov_b64_e32 v[36:37], 0
	v_mov_b64_e32 v[38:39], 0
	v_mov_b64_e32 v[72:73], 0
	v_mov_b64_e32 v[74:75], 0
	v_mov_b64_e32 v[44:45], 0
	v_mov_b64_e32 v[46:47], 0
	v_mov_b64_e32 v[84:85], 0
	v_mov_b64_e32 v[86:87], 0
	v_mov_b64_e32 v[52:53], 0
	v_mov_b64_e32 v[54:55], 0
	v_mov_b64_e32 v[92:93], 0
	v_mov_b64_e32 v[94:95], 0
	v_mov_b64_e32 v[60:61], 0
	v_mov_b64_e32 v[62:63], 0
	v_mov_b64_e32 v[100:101], 0
	v_mov_b64_e32 v[102:103], 0

; template <class Epi, class Sched, bool ALIGN_EPI = false, bool SP2 = false>
; __device__ __forceinline__ void gemm_phase(PG8_LAS unsigned char* lds, const Gemm g, const Sched& S, const Epi& E) {
;     ...
;         for (int a = 0; a < 2; ++a)
; #pragma unroll
;             for (int b = 0; b < 2; ++b)
; #pragma unroll
;                 for (int m = 0; m < 4; ++m)
; #pragma unroll
;                     for (int n = 0; n < 2; ++n) acc[a][b][m][n] = (f32x4){0.f, 0.f, 0.f, 0.f};
;         cur = nxt; cA = nA; cB = nB; ++ui;
.LBB0_1097:
	s_add_u32 s52, s26, 0x100
	v_mov_b32_e32 v0, 0
	s_addc_u32 s53, s27, 0
	s_mov_b32 s54, -2
	v_mov_b32_e32 v1, 0
	v_mov_b64_e32 v[2:3], 0
	v_mov_b64_e32 v[4:5], 0
	v_mov_b64_e32 v[6:7], 0
	v_mov_b64_e32 v[8:9], 0
	v_mov_b64_e32 v[10:11], 0
	v_mov_b64_e32 v[16:17], 0
	v_mov_b64_e32 v[18:19], 0
	v_mov_b64_e32 v[24:25], 0
	v_mov_b64_e32 v[26:27], 0
	v_mov_b64_e32 v[32:33], 0
	v_mov_b64_e32 v[34:35], 0
	v_mov_b64_e32 v[40:41], 0
	v_mov_b64_e32 v[42:43], 0
	v_mov_b64_e32 v[48:49], 0
	v_mov_b64_e32 v[50:51], 0
	v_mov_b64_e32 v[12:13], 0
	v_mov_b64_e32 v[14:15], 0
	v_mov_b64_e32 v[20:21], 0
	v_mov_b64_e32 v[22:23], 0
	v_mov_b64_e32 v[28:29], 0
	v_mov_b64_e32 v[30:31], 0
	v_mov_b64_e32 v[36:37], 0
	v_mov_b64_e32 v[38:39], 0
	v_mov_b64_e32 v[44:45], 0
	v_mov_b64_e32 v[46:47], 0
	v_mov_b64_e32 v[52:53], 0
	v_mov_b64_e32 v[54:55], 0
	v_mov_b64_e32 v[56:57], 0
	v_mov_b64_e32 v[58:59], 0
	v_mov_b64_e32 v[60:61], 0
	v_mov_b64_e32 v[62:63], 0
	v_mov_b64_e32 v[64:65], 0
	v_mov_b64_e32 v[66:67], 0
	v_mov_b64_e32 v[68:69], 0
	v_mov_b64_e32 v[70:71], 0
	v_mov_b64_e32 v[72:73], 0
	v_mov_b64_e32 v[74:75], 0
	v_mov_b64_e32 v[76:77], 0
	v_mov_b64_e32 v[78:79], 0
	v_mov_b64_e32 v[84:85], 0
	v_mov_b64_e32 v[86:87], 0
	v_mov_b64_e32 v[92:93], 0
	v_mov_b64_e32 v[94:95], 0
	v_mov_b64_e32 v[100:101], 0
	v_mov_b64_e32 v[102:103], 0
	v_mov_b64_e32 v[108:109], 0
	v_mov_b64_e32 v[110:111], 0
	v_mov_b64_e32 v[80:81], 0
	v_mov_b64_e32 v[82:83], 0
	v_mov_b64_e32 v[88:89], 0
	v_mov_b64_e32 v[90:91], 0
	v_mov_b64_e32 v[96:97], 0
	v_mov_b64_e32 v[98:99], 0
	v_mov_b64_e32 v[104:105], 0
	v_mov_b64_e32 v[106:107], 0
	v_mov_b64_e32 v[112:113], 0
	v_mov_b64_e32 v[114:115], 0
	v_mov_b64_e32 v[116:117], 0
	v_mov_b64_e32 v[118:119], 0
	v_mov_b64_e32 v[120:121], 0
	v_mov_b64_e32 v[122:123], 0
	v_mov_b64_e32 v[124:125], 0
	v_mov_b64_e32 v[126:127], 0
